# kind-1 epilogue: rstd loads issued first (before address setup and relu^2), scaling by rstd^2 after relu^2 for the MLP up-projection so the load latency is covered
# speedup vs baseline: 1.0050x; 1.0050x over previous
.LBB0_678:
	v_readlane_b32 s20, v254, 35
	v_lshl_add_u32 v112, s53, 8, v146
	v_lshlrev_b32_e32 v112, 2, v112
	s_and_b32 s21, s20, 1
	s_cmp_eq_u32 s21, 1
	s_cselect_b32 s21, 4, 8
	s_cmp_eq_u32 s78, s21
	s_cselect_b64 s[38:39], -1, 0
	s_cmp_eq_u32 s78, 0
	s_cselect_b64 vcc, -1, 0
	s_cmp_lg_u32 s20, 0
	s_cselect_b64 s[20:21], -1, 0
	s_and_b64 vcc, vcc, s[20:21]
	s_or_b64 s[38:39], s[38:39], vcc
	s_and_b64 vcc, exec, s[38:39]
	s_cbranch_vccz .Lg1e_noload
	v_add_u32_e32 v114, 0x4308000, v112
	global_load_dword v192, v114, s[68:69]
	global_load_dword v194, v114, s[68:69] offset:64
	global_load_dword v196, v114, s[68:69] offset:128
	global_load_dword v198, v114, s[68:69] offset:192
	global_load_dword v200, v114, s[68:69] offset:512
	global_load_dword v202, v114, s[68:69] offset:576
	global_load_dword v204, v114, s[68:69] offset:640
	global_load_dword v206, v114, s[68:69] offset:704
.Lg1e_noload:
	v_lshrrev_b32_e32 v112, 6, v146
	v_bfe_u32 v114, v148, 5, 2
	v_lshl_add_u32 v112, v112, 2, v114
	v_mul_u32_u24_e32 v112, 2304, v112
	v_add_u32_e32 v112, 135424, v112
	v_and_b32_e32 v114, 15, v189
	v_mul_u32_u24_e32 v114, 144, v114
	v_lshrrev_b32_e32 v115, 4, v189
	v_lshl_add_u32 v114, v115, 4, v114
	v_add_u32_e32 v190, v112, v114
	v_lshrrev_b32_e32 v114, 3, v189
	v_and_b32_e32 v115, 7, v189
	v_mul_u32_u24_e32 v191, 144, v114
	v_lshl_add_u32 v191, v115, 4, v191
	v_add_u32_e32 v191, v112, v191
	v_and_b32_e32 v112, 0xfffffff0, v146
	v_add_u32_e32 v112, v112, v114
	v_lshl_add_u32 v112, s53, 8, v112
	v_and_b32_e32 v114, 0x60, v148
	v_lshl_add_u32 v114, v114, 1, 0
	v_lshl_add_u32 v114, v115, 3, v114
	v_lshl_add_u32 v114, s52, 8, v114
	v_mad_u32_u24 v144, v112, s6, v114
	s_lshl_b32 s21, s6, 4
	v_lshlrev_b32_e32 v144, 1, v144
	v_add_u32_e32 v145, s21, v144
	s_andn2_b64 vcc, exec, s[4:5]
	s_cbranch_vccnz .Lg1e_norelu1
	v_max_f32_e32 v0, 0, v0
	v_max_f32_e32 v1, 0, v1
	v_max_f32_e32 v2, 0, v2
	v_max_f32_e32 v3, 0, v3
	v_max_f32_e32 v4, 0, v4
	v_max_f32_e32 v5, 0, v5
	v_max_f32_e32 v6, 0, v6
	v_max_f32_e32 v7, 0, v7
	v_max_f32_e32 v8, 0, v8
	v_max_f32_e32 v9, 0, v9
	v_max_f32_e32 v10, 0, v10
	v_max_f32_e32 v11, 0, v11
	v_max_f32_e32 v12, 0, v12
	v_max_f32_e32 v13, 0, v13
	v_max_f32_e32 v14, 0, v14
	v_max_f32_e32 v15, 0, v15
	v_max_f32_e32 v16, 0, v16
	v_max_f32_e32 v17, 0, v17
	v_max_f32_e32 v18, 0, v18
	v_max_f32_e32 v19, 0, v19
	v_max_f32_e32 v20, 0, v20
	v_max_f32_e32 v21, 0, v21
	v_max_f32_e32 v22, 0, v22
	v_max_f32_e32 v23, 0, v23
	v_max_f32_e32 v24, 0, v24
	v_max_f32_e32 v25, 0, v25
	v_max_f32_e32 v26, 0, v26
	v_max_f32_e32 v27, 0, v27
	v_max_f32_e32 v28, 0, v28
	v_max_f32_e32 v29, 0, v29
	v_max_f32_e32 v30, 0, v30
	v_max_f32_e32 v31, 0, v31
	v_max_f32_e32 v32, 0, v32
	v_max_f32_e32 v33, 0, v33
	v_max_f32_e32 v34, 0, v34
	v_max_f32_e32 v35, 0, v35
	v_max_f32_e32 v36, 0, v36
	v_max_f32_e32 v37, 0, v37
	v_max_f32_e32 v38, 0, v38
	v_max_f32_e32 v39, 0, v39
	v_max_f32_e32 v40, 0, v40
	v_max_f32_e32 v41, 0, v41
	v_max_f32_e32 v42, 0, v42
	v_max_f32_e32 v43, 0, v43
	v_max_f32_e32 v44, 0, v44
	v_max_f32_e32 v45, 0, v45
	v_max_f32_e32 v46, 0, v46
	v_max_f32_e32 v47, 0, v47
	v_max_f32_e32 v48, 0, v48
	v_max_f32_e32 v49, 0, v49
	v_max_f32_e32 v50, 0, v50
	v_max_f32_e32 v51, 0, v51
	v_max_f32_e32 v52, 0, v52
	v_max_f32_e32 v53, 0, v53
	v_max_f32_e32 v54, 0, v54
	v_max_f32_e32 v55, 0, v55
	v_max_f32_e32 v56, 0, v56
	v_max_f32_e32 v57, 0, v57
	v_max_f32_e32 v58, 0, v58
	v_max_f32_e32 v59, 0, v59
	v_max_f32_e32 v60, 0, v60
	v_max_f32_e32 v61, 0, v61
	v_max_f32_e32 v62, 0, v62
	v_max_f32_e32 v63, 0, v63
	v_max_f32_e32 v64, 0, v64
	v_max_f32_e32 v65, 0, v65
	v_max_f32_e32 v66, 0, v66
	v_max_f32_e32 v67, 0, v67
	v_max_f32_e32 v68, 0, v68
	v_max_f32_e32 v69, 0, v69
	v_max_f32_e32 v70, 0, v70
	v_max_f32_e32 v71, 0, v71
	v_max_f32_e32 v72, 0, v72
	v_max_f32_e32 v73, 0, v73
	v_max_f32_e32 v74, 0, v74
	v_max_f32_e32 v75, 0, v75
	v_max_f32_e32 v76, 0, v76
	v_max_f32_e32 v77, 0, v77
	v_max_f32_e32 v78, 0, v78
	v_max_f32_e32 v79, 0, v79
	v_max_f32_e32 v80, 0, v80
	v_max_f32_e32 v81, 0, v81
	v_max_f32_e32 v82, 0, v82
	v_max_f32_e32 v83, 0, v83
	v_max_f32_e32 v84, 0, v84
	v_max_f32_e32 v85, 0, v85
	v_max_f32_e32 v86, 0, v86
	v_max_f32_e32 v87, 0, v87
	v_max_f32_e32 v88, 0, v88
	v_max_f32_e32 v89, 0, v89
	v_max_f32_e32 v90, 0, v90
	v_max_f32_e32 v91, 0, v91
	v_max_f32_e32 v92, 0, v92
	v_max_f32_e32 v93, 0, v93
	v_max_f32_e32 v94, 0, v94
	v_max_f32_e32 v95, 0, v95
	v_max_f32_e32 v96, 0, v96
	v_max_f32_e32 v97, 0, v97
	v_max_f32_e32 v98, 0, v98
	v_max_f32_e32 v99, 0, v99
	v_max_f32_e32 v100, 0, v100
	v_max_f32_e32 v101, 0, v101
	v_max_f32_e32 v102, 0, v102
	v_max_f32_e32 v103, 0, v103
	v_max_f32_e32 v104, 0, v104
	v_max_f32_e32 v105, 0, v105
	v_max_f32_e32 v106, 0, v106
	v_max_f32_e32 v107, 0, v107
	v_max_f32_e32 v108, 0, v108
	v_max_f32_e32 v109, 0, v109
	v_max_f32_e32 v110, 0, v110
	v_max_f32_e32 v111, 0, v111
	v_max_f32_e32 v116, 0, v116
	v_max_f32_e32 v117, 0, v117
	v_max_f32_e32 v118, 0, v118
	v_max_f32_e32 v119, 0, v119
	v_max_f32_e32 v120, 0, v120
	v_max_f32_e32 v121, 0, v121
	v_max_f32_e32 v122, 0, v122
	v_max_f32_e32 v123, 0, v123
	v_max_f32_e32 v124, 0, v124
	v_max_f32_e32 v125, 0, v125
	v_max_f32_e32 v126, 0, v126
	v_max_f32_e32 v127, 0, v127
	v_max_f32_e32 v128, 0, v128
	v_max_f32_e32 v129, 0, v129
	v_max_f32_e32 v130, 0, v130
	v_max_f32_e32 v131, 0, v131
	v_pk_mul_f32 v[0:1], v[0:1], v[0:1]
	v_pk_mul_f32 v[2:3], v[2:3], v[2:3]
	v_pk_mul_f32 v[4:5], v[4:5], v[4:5]
	v_pk_mul_f32 v[6:7], v[6:7], v[6:7]
	v_pk_mul_f32 v[8:9], v[8:9], v[8:9]
	v_pk_mul_f32 v[10:11], v[10:11], v[10:11]
	v_pk_mul_f32 v[12:13], v[12:13], v[12:13]
	v_pk_mul_f32 v[14:15], v[14:15], v[14:15]
	v_pk_mul_f32 v[16:17], v[16:17], v[16:17]
	v_pk_mul_f32 v[18:19], v[18:19], v[18:19]
	v_pk_mul_f32 v[20:21], v[20:21], v[20:21]
	v_pk_mul_f32 v[22:23], v[22:23], v[22:23]
	v_pk_mul_f32 v[24:25], v[24:25], v[24:25]
	v_pk_mul_f32 v[26:27], v[26:27], v[26:27]
	v_pk_mul_f32 v[28:29], v[28:29], v[28:29]
	v_pk_mul_f32 v[30:31], v[30:31], v[30:31]
	v_pk_mul_f32 v[32:33], v[32:33], v[32:33]
	v_pk_mul_f32 v[34:35], v[34:35], v[34:35]
	v_pk_mul_f32 v[36:37], v[36:37], v[36:37]
	v_pk_mul_f32 v[38:39], v[38:39], v[38:39]
	v_pk_mul_f32 v[40:41], v[40:41], v[40:41]
	v_pk_mul_f32 v[42:43], v[42:43], v[42:43]
	v_pk_mul_f32 v[44:45], v[44:45], v[44:45]
	v_pk_mul_f32 v[46:47], v[46:47], v[46:47]
	v_pk_mul_f32 v[48:49], v[48:49], v[48:49]
	v_pk_mul_f32 v[50:51], v[50:51], v[50:51]
	v_pk_mul_f32 v[52:53], v[52:53], v[52:53]
	v_pk_mul_f32 v[54:55], v[54:55], v[54:55]
	v_pk_mul_f32 v[56:57], v[56:57], v[56:57]
	v_pk_mul_f32 v[58:59], v[58:59], v[58:59]
	v_pk_mul_f32 v[60:61], v[60:61], v[60:61]
	v_pk_mul_f32 v[62:63], v[62:63], v[62:63]
	v_pk_mul_f32 v[64:65], v[64:65], v[64:65]
	v_pk_mul_f32 v[66:67], v[66:67], v[66:67]
	v_pk_mul_f32 v[68:69], v[68:69], v[68:69]
	v_pk_mul_f32 v[70:71], v[70:71], v[70:71]
	v_pk_mul_f32 v[72:73], v[72:73], v[72:73]
	v_pk_mul_f32 v[74:75], v[74:75], v[74:75]
	v_pk_mul_f32 v[76:77], v[76:77], v[76:77]
	v_pk_mul_f32 v[78:79], v[78:79], v[78:79]
	v_pk_mul_f32 v[80:81], v[80:81], v[80:81]
	v_pk_mul_f32 v[82:83], v[82:83], v[82:83]
	v_pk_mul_f32 v[84:85], v[84:85], v[84:85]
	v_pk_mul_f32 v[86:87], v[86:87], v[86:87]
	v_pk_mul_f32 v[88:89], v[88:89], v[88:89]
	v_pk_mul_f32 v[90:91], v[90:91], v[90:91]
	v_pk_mul_f32 v[92:93], v[92:93], v[92:93]
	v_pk_mul_f32 v[94:95], v[94:95], v[94:95]
	v_pk_mul_f32 v[96:97], v[96:97], v[96:97]
	v_pk_mul_f32 v[98:99], v[98:99], v[98:99]
	v_pk_mul_f32 v[100:101], v[100:101], v[100:101]
	v_pk_mul_f32 v[102:103], v[102:103], v[102:103]
	v_pk_mul_f32 v[104:105], v[104:105], v[104:105]
	v_pk_mul_f32 v[106:107], v[106:107], v[106:107]
	v_pk_mul_f32 v[108:109], v[108:109], v[108:109]
	v_pk_mul_f32 v[110:111], v[110:111], v[110:111]
	v_pk_mul_f32 v[116:117], v[116:117], v[116:117]
	v_pk_mul_f32 v[118:119], v[118:119], v[118:119]
	v_pk_mul_f32 v[120:121], v[120:121], v[120:121]
	v_pk_mul_f32 v[122:123], v[122:123], v[122:123]
	v_pk_mul_f32 v[124:125], v[124:125], v[124:125]
	v_pk_mul_f32 v[126:127], v[126:127], v[126:127]
	v_pk_mul_f32 v[128:129], v[128:129], v[128:129]
	v_pk_mul_f32 v[130:131], v[130:131], v[130:131]
.Lg1e_norelu1:
	s_and_b64 vcc, exec, s[38:39]
	s_cbranch_vccz .Lg1e_norelu
	s_waitcnt vmcnt(0)
	s_andn2_b64 vcc, exec, s[4:5]
	s_cbranch_vccnz .Lg1e_lin
	v_mul_f32_e32 v192, v192, v192
	v_mul_f32_e32 v194, v194, v194
	v_mul_f32_e32 v196, v196, v196
	v_mul_f32_e32 v198, v198, v198
	v_mul_f32_e32 v200, v200, v200
	v_mul_f32_e32 v202, v202, v202
	v_mul_f32_e32 v204, v204, v204
	v_mul_f32_e32 v206, v206, v206
.Lg1e_lin:
	v_pk_mul_f32 v[116:117], v[116:117], v[192:193] op_sel_hi:[1,0]
	v_pk_mul_f32 v[118:119], v[118:119], v[192:193] op_sel_hi:[1,0]
	v_pk_mul_f32 v[120:121], v[120:121], v[192:193] op_sel_hi:[1,0]
	v_pk_mul_f32 v[122:123], v[122:123], v[192:193] op_sel_hi:[1,0]
	v_pk_mul_f32 v[124:125], v[124:125], v[192:193] op_sel_hi:[1,0]
	v_pk_mul_f32 v[126:127], v[126:127], v[192:193] op_sel_hi:[1,0]
	v_pk_mul_f32 v[128:129], v[128:129], v[192:193] op_sel_hi:[1,0]
	v_pk_mul_f32 v[130:131], v[130:131], v[192:193] op_sel_hi:[1,0]
	v_pk_mul_f32 v[96:97], v[96:97], v[194:195] op_sel_hi:[1,0]
	v_pk_mul_f32 v[98:99], v[98:99], v[194:195] op_sel_hi:[1,0]
	v_pk_mul_f32 v[100:101], v[100:101], v[194:195] op_sel_hi:[1,0]
	v_pk_mul_f32 v[102:103], v[102:103], v[194:195] op_sel_hi:[1,0]
	v_pk_mul_f32 v[104:105], v[104:105], v[194:195] op_sel_hi:[1,0]
	v_pk_mul_f32 v[106:107], v[106:107], v[194:195] op_sel_hi:[1,0]
	v_pk_mul_f32 v[108:109], v[108:109], v[194:195] op_sel_hi:[1,0]
	v_pk_mul_f32 v[110:111], v[110:111], v[194:195] op_sel_hi:[1,0]
	v_pk_mul_f32 v[80:81], v[80:81], v[196:197] op_sel_hi:[1,0]
	v_pk_mul_f32 v[82:83], v[82:83], v[196:197] op_sel_hi:[1,0]
	v_pk_mul_f32 v[84:85], v[84:85], v[196:197] op_sel_hi:[1,0]
	v_pk_mul_f32 v[86:87], v[86:87], v[196:197] op_sel_hi:[1,0]
	v_pk_mul_f32 v[88:89], v[88:89], v[196:197] op_sel_hi:[1,0]
	v_pk_mul_f32 v[90:91], v[90:91], v[196:197] op_sel_hi:[1,0]
	v_pk_mul_f32 v[92:93], v[92:93], v[196:197] op_sel_hi:[1,0]
	v_pk_mul_f32 v[94:95], v[94:95], v[196:197] op_sel_hi:[1,0]
	v_pk_mul_f32 v[64:65], v[64:65], v[198:199] op_sel_hi:[1,0]
	v_pk_mul_f32 v[66:67], v[66:67], v[198:199] op_sel_hi:[1,0]
	v_pk_mul_f32 v[68:69], v[68:69], v[198:199] op_sel_hi:[1,0]
	v_pk_mul_f32 v[70:71], v[70:71], v[198:199] op_sel_hi:[1,0]
	v_pk_mul_f32 v[72:73], v[72:73], v[198:199] op_sel_hi:[1,0]
	v_pk_mul_f32 v[74:75], v[74:75], v[198:199] op_sel_hi:[1,0]
	v_pk_mul_f32 v[76:77], v[76:77], v[198:199] op_sel_hi:[1,0]
	v_pk_mul_f32 v[78:79], v[78:79], v[198:199] op_sel_hi:[1,0]
	v_pk_mul_f32 v[48:49], v[48:49], v[200:201] op_sel_hi:[1,0]
	v_pk_mul_f32 v[50:51], v[50:51], v[200:201] op_sel_hi:[1,0]
	v_pk_mul_f32 v[52:53], v[52:53], v[200:201] op_sel_hi:[1,0]
	v_pk_mul_f32 v[54:55], v[54:55], v[200:201] op_sel_hi:[1,0]
	v_pk_mul_f32 v[56:57], v[56:57], v[200:201] op_sel_hi:[1,0]
	v_pk_mul_f32 v[58:59], v[58:59], v[200:201] op_sel_hi:[1,0]
	v_pk_mul_f32 v[60:61], v[60:61], v[200:201] op_sel_hi:[1,0]
	v_pk_mul_f32 v[62:63], v[62:63], v[200:201] op_sel_hi:[1,0]
	v_pk_mul_f32 v[32:33], v[32:33], v[202:203] op_sel_hi:[1,0]
	v_pk_mul_f32 v[34:35], v[34:35], v[202:203] op_sel_hi:[1,0]
	v_pk_mul_f32 v[36:37], v[36:37], v[202:203] op_sel_hi:[1,0]
	v_pk_mul_f32 v[38:39], v[38:39], v[202:203] op_sel_hi:[1,0]
	v_pk_mul_f32 v[40:41], v[40:41], v[202:203] op_sel_hi:[1,0]
	v_pk_mul_f32 v[42:43], v[42:43], v[202:203] op_sel_hi:[1,0]
	v_pk_mul_f32 v[44:45], v[44:45], v[202:203] op_sel_hi:[1,0]
	v_pk_mul_f32 v[46:47], v[46:47], v[202:203] op_sel_hi:[1,0]
	v_pk_mul_f32 v[16:17], v[16:17], v[204:205] op_sel_hi:[1,0]
	v_pk_mul_f32 v[18:19], v[18:19], v[204:205] op_sel_hi:[1,0]
	v_pk_mul_f32 v[20:21], v[20:21], v[204:205] op_sel_hi:[1,0]
	v_pk_mul_f32 v[22:23], v[22:23], v[204:205] op_sel_hi:[1,0]
	v_pk_mul_f32 v[24:25], v[24:25], v[204:205] op_sel_hi:[1,0]
	v_pk_mul_f32 v[26:27], v[26:27], v[204:205] op_sel_hi:[1,0]
	v_pk_mul_f32 v[28:29], v[28:29], v[204:205] op_sel_hi:[1,0]
	v_pk_mul_f32 v[30:31], v[30:31], v[204:205] op_sel_hi:[1,0]
	v_pk_mul_f32 v[0:1], v[0:1], v[206:207] op_sel_hi:[1,0]
	v_pk_mul_f32 v[2:3], v[2:3], v[206:207] op_sel_hi:[1,0]
	v_pk_mul_f32 v[4:5], v[4:5], v[206:207] op_sel_hi:[1,0]
	v_pk_mul_f32 v[6:7], v[6:7], v[206:207] op_sel_hi:[1,0]
	v_pk_mul_f32 v[8:9], v[8:9], v[206:207] op_sel_hi:[1,0]
	v_pk_mul_f32 v[10:11], v[10:11], v[206:207] op_sel_hi:[1,0]
	v_pk_mul_f32 v[12:13], v[12:13], v[206:207] op_sel_hi:[1,0]
	v_pk_mul_f32 v[14:15], v[14:15], v[206:207] op_sel_hi:[1,0]
